# v7 + GEMM K-loop ds_read bases hoisted, wait pairs merged, attention lane address parts hoisted per unit (trans-hazard pad restored)
# speedup vs baseline: 1.0069x; 1.0069x over previous
.LBB0_121:
	s_mul_i32 s8, s20, 0x4400
	s_mul_i32 s9, s20, 0x5000
	s_sub_i32 s8, s8, s28
	s_add_i32 s11, s11, 1
	v_add_u32_e32 v164, s8, v165
	v_add_u32_e32 v162, s9, v163
	ds_read_b128 v[128:131], v164
	ds_read_b128 v[132:135], v164 offset:8704
	ds_read_b128 v[136:139], v165
	ds_read_b128 v[176:179], v164 offset:32
	ds_read_b128 v[180:183], v164 offset:8736
	ds_read_b128 v[184:187], v165 offset:32
	s_waitcnt lgkmcnt(3)
	s_setprio 1
	v_mfma_f32_32x32x16_bf16 v[144:159], v[128:131], v[136:139], 0
	v_mfma_f32_32x32x16_bf16 v[128:143], v[132:135], v[136:139], 0
	s_setprio 0
	ds_read_b128 v[188:191], v164 offset:64
	ds_read_b128 v[192:195], v164 offset:8768
	ds_read_b128 v[196:199], v165 offset:64
	s_waitcnt lgkmcnt(3)
	s_setprio 1
	v_mfma_f32_32x32x16_bf16 v[144:159], v[176:179], v[184:187], v[144:159]
	v_mfma_f32_32x32x16_bf16 v[128:143], v[180:183], v[184:187], v[128:143]
	s_setprio 0
	ds_read_b128 v[200:203], v164 offset:96
	ds_read_b128 v[204:207], v164 offset:8800
	ds_read_b128 v[208:211], v165 offset:96
	s_waitcnt lgkmcnt(3)
	s_setprio 1
	v_mfma_f32_32x32x16_bf16 v[144:159], v[188:191], v[196:199], v[144:159]
	v_mfma_f32_32x32x16_bf16 v[128:143], v[192:195], v[196:199], v[128:143]
	s_setprio 0
	s_waitcnt lgkmcnt(0)
	s_setprio 1
	v_mfma_f32_32x32x16_bf16 v[144:159], v[200:203], v[208:211], v[144:159]
	v_mfma_f32_32x32x16_bf16 v[128:143], v[204:207], v[208:211], v[128:143]
	s_setprio 0
	ds_read_b128 v[208:211], v164 offset:128
	ds_read_b128 v[212:215], v164 offset:8832
	ds_read_b128 v[250:253], v165 offset:128
	ds_read_b128 v[166:169], v164 offset:160
	ds_read_b128 v[232:235], v164 offset:8864
	ds_read_b128 v[246:249], v165 offset:160
	ds_read_b64_tr_b16 v[224:225], v162 offset:34816
	ds_read_b64_tr_b16 v[226:227], v162 offset:37376
	ds_read_b64_tr_b16 v[228:229], v162 offset:34880
	ds_read_b64_tr_b16 v[230:231], v162 offset:37440
	s_waitcnt lgkmcnt(7)
	s_setprio 1
	v_mfma_f32_32x32x16_bf16 v[176:191], v[208:211], v[250:253], 0
	v_mfma_f32_32x32x16_bf16 v[192:207], v[212:215], v[250:253], 0
	s_setprio 0
	ds_read_b128 v[208:211], v164 offset:192
	ds_read_b128 v[212:215], v164 offset:8896
	ds_read_b128 v[250:253], v165 offset:192
	v_exp_f32_e32 v144, v144
	v_exp_f32_e32 v145, v145
	s_nop 0
	v_add_f32_e32 v170, v144, v145
	v_cvt_pk_bf16_f32 v144, v144, v145
	s_waitcnt lgkmcnt(7)
	s_setprio 1
	v_mfma_f32_32x32x16_bf16 v[176:191], v[166:169], v[246:249], v[176:191]
	v_mfma_f32_32x32x16_bf16 v[192:207], v[232:235], v[246:249], v[192:207]
	s_setprio 0
	ds_read_b128 v[166:169], v164 offset:224
	ds_read_b128 v[232:235], v164 offset:8928
	ds_read_b128 v[246:249], v165 offset:224
	v_exp_f32_e32 v146, v146
	v_exp_f32_e32 v147, v147
	s_nop 0
	v_add_f32_e32 v171, v146, v147
	v_cvt_pk_bf16_f32 v145, v146, v147
	s_waitcnt lgkmcnt(3)
	s_setprio 1
	v_mfma_f32_32x32x16_bf16 v[176:191], v[208:211], v[250:253], v[176:191]
	v_mfma_f32_32x32x16_bf16 v[192:207], v[212:215], v[250:253], v[192:207]
	s_setprio 0
	v_exp_f32_e32 v148, v148
	v_exp_f32_e32 v149, v149
	s_nop 0
	v_add_f32_e32 v172, v148, v149
	v_cvt_pk_bf16_f32 v146, v148, v149
	s_waitcnt lgkmcnt(0)
	s_setprio 1
	v_mfma_f32_32x32x16_bf16 v[176:191], v[166:169], v[246:249], v[176:191]
	v_mfma_f32_32x32x16_bf16 v[192:207], v[232:235], v[246:249], v[192:207]
	s_setprio 0
	ds_read_b64_tr_b16 v[232:233], v162 offset:34944
	ds_read_b64_tr_b16 v[234:235], v162 offset:37504
	ds_read_b64_tr_b16 v[246:247], v162 offset:35008
	ds_read_b64_tr_b16 v[248:249], v162 offset:37568
	v_exp_f32_e32 v150, v150
	v_exp_f32_e32 v151, v151
	s_nop 0
	v_add_f32_e32 v173, v150, v151
	v_cvt_pk_bf16_f32 v147, v150, v151
	v_add_f32_e32 v170, v170, v171
	v_add_f32_e32 v172, v172, v173
	v_add_f32_e32 v170, v170, v172
	v_add_f32_e32 v174, v174, v170
	s_waitcnt lgkmcnt(0)
	s_setprio 1
	v_mfma_f32_32x32x16_bf16 v[112:127], v[144:147], v[224:227], v[112:127]
	v_exp_f32_e32 v176, v176
	v_exp_f32_e32 v177, v177
	ds_read_b64_tr_b16 v[208:209], v162 offset:39936
	ds_read_b64_tr_b16 v[210:211], v162 offset:42496
	v_add_f32_e32 v170, v176, v177
	v_cvt_pk_bf16_f32 v176, v176, v177
	v_mfma_f32_32x32x16_bf16 v[96:111], v[144:147], v[228:231], v[96:111]
	v_exp_f32_e32 v178, v178
	v_exp_f32_e32 v179, v179
	s_nop 0
	v_add_f32_e32 v171, v178, v179
	v_cvt_pk_bf16_f32 v177, v178, v179
	v_mfma_f32_32x32x16_bf16 v[80:95], v[144:147], v[232:235], v[80:95]
	v_exp_f32_e32 v180, v180
	v_exp_f32_e32 v181, v181
	ds_read_b64_tr_b16 v[212:213], v162 offset:40000
	ds_read_b64_tr_b16 v[214:215], v162 offset:42560
	v_add_f32_e32 v172, v180, v181
	v_cvt_pk_bf16_f32 v178, v180, v181
	v_mfma_f32_32x32x16_bf16 v[64:79], v[144:147], v[246:249], v[64:79]
	v_exp_f32_e32 v182, v182
	v_exp_f32_e32 v183, v183
	s_nop 0
	v_add_f32_e32 v173, v182, v183
	v_cvt_pk_bf16_f32 v179, v182, v183
	s_setprio 0
	v_add_f32_e32 v170, v170, v171
	v_add_f32_e32 v172, v172, v173
	v_add_f32_e32 v170, v170, v172
	v_add_f32_e32 v175, v175, v170
	s_waitcnt lgkmcnt(4)
	s_setprio 1
	v_mfma_f32_32x32x16_bf16 v[48:63], v[176:179], v[224:227], v[48:63]
	v_exp_f32_e32 v152, v152
	v_exp_f32_e32 v153, v153
	ds_read_b64_tr_b16 v[250:251], v162 offset:40064
	ds_read_b64_tr_b16 v[252:253], v162 offset:42624
	v_add_f32_e32 v170, v152, v153
	v_cvt_pk_bf16_f32 v152, v152, v153
	v_mfma_f32_32x32x16_bf16 v[32:47], v[176:179], v[228:231], v[32:47]
	v_exp_f32_e32 v154, v154
	v_exp_f32_e32 v155, v155
	s_nop 0
	v_add_f32_e32 v171, v154, v155
	v_cvt_pk_bf16_f32 v153, v154, v155
	v_mfma_f32_32x32x16_bf16 v[16:31], v[176:179], v[232:235], v[16:31]
	v_exp_f32_e32 v156, v156
	v_exp_f32_e32 v157, v157
	ds_read_b64_tr_b16 v[166:167], v162 offset:40128
	ds_read_b64_tr_b16 v[168:169], v162 offset:42688
	v_add_f32_e32 v172, v156, v157
	v_cvt_pk_bf16_f32 v154, v156, v157
	v_mfma_f32_32x32x16_bf16 v[0:15], v[176:179], v[246:249], v[0:15]
	v_exp_f32_e32 v158, v158
	v_exp_f32_e32 v159, v159
	s_nop 0
	v_add_f32_e32 v173, v158, v159
	v_cvt_pk_bf16_f32 v155, v158, v159
	s_setprio 0
	v_add_f32_e32 v170, v170, v171
	v_add_f32_e32 v172, v172, v173
	v_add_f32_e32 v170, v170, v172
	v_add_f32_e32 v174, v174, v170
	s_waitcnt lgkmcnt(0)
	s_setprio 1
	v_mfma_f32_32x32x16_bf16 v[112:127], v[152:155], v[208:211], v[112:127]
	v_exp_f32_e32 v184, v184
	v_exp_f32_e32 v185, v185
	ds_read_b64_tr_b16 v[224:225], v162 offset:45056
	ds_read_b64_tr_b16 v[226:227], v162 offset:47616
	v_add_f32_e32 v170, v184, v185
	v_cvt_pk_bf16_f32 v184, v184, v185
	v_mfma_f32_32x32x16_bf16 v[96:111], v[152:155], v[212:215], v[96:111]
	v_exp_f32_e32 v186, v186
	v_exp_f32_e32 v187, v187
	s_nop 0
	v_add_f32_e32 v171, v186, v187
	v_cvt_pk_bf16_f32 v185, v186, v187
	v_mfma_f32_32x32x16_bf16 v[80:95], v[152:155], v[250:253], v[80:95]
	v_exp_f32_e32 v188, v188
	v_exp_f32_e32 v189, v189
	ds_read_b64_tr_b16 v[228:229], v162 offset:45120
	ds_read_b64_tr_b16 v[230:231], v162 offset:47680
	v_add_f32_e32 v172, v188, v189
	v_cvt_pk_bf16_f32 v186, v188, v189
	v_mfma_f32_32x32x16_bf16 v[64:79], v[152:155], v[166:169], v[64:79]
	v_exp_f32_e32 v190, v190
	v_exp_f32_e32 v191, v191
	s_nop 0
	v_add_f32_e32 v173, v190, v191
	v_cvt_pk_bf16_f32 v187, v190, v191
	s_setprio 0
	v_add_f32_e32 v170, v170, v171
	v_add_f32_e32 v172, v172, v173
	v_add_f32_e32 v170, v170, v172
	v_add_f32_e32 v175, v175, v170
	s_waitcnt lgkmcnt(4)
	s_setprio 1
	v_mfma_f32_32x32x16_bf16 v[48:63], v[184:187], v[208:211], v[48:63]
	v_exp_f32_e32 v128, v128
	v_exp_f32_e32 v129, v129
	ds_read_b64_tr_b16 v[232:233], v162 offset:45184
	ds_read_b64_tr_b16 v[234:235], v162 offset:47744
	v_add_f32_e32 v170, v128, v129
	v_cvt_pk_bf16_f32 v128, v128, v129
	v_mfma_f32_32x32x16_bf16 v[32:47], v[184:187], v[212:215], v[32:47]
	v_exp_f32_e32 v130, v130
	v_exp_f32_e32 v131, v131
	s_nop 0
	v_add_f32_e32 v171, v130, v131
	v_cvt_pk_bf16_f32 v129, v130, v131
	v_mfma_f32_32x32x16_bf16 v[16:31], v[184:187], v[250:253], v[16:31]
	v_exp_f32_e32 v132, v132
	v_exp_f32_e32 v133, v133
	ds_read_b64_tr_b16 v[246:247], v162 offset:45248
	ds_read_b64_tr_b16 v[248:249], v162 offset:47808
	v_add_f32_e32 v172, v132, v133
	v_cvt_pk_bf16_f32 v130, v132, v133
	v_mfma_f32_32x32x16_bf16 v[0:15], v[184:187], v[166:169], v[0:15]
	v_exp_f32_e32 v134, v134
	v_exp_f32_e32 v135, v135
	s_nop 0
	v_add_f32_e32 v173, v134, v135
	v_cvt_pk_bf16_f32 v131, v134, v135
	s_setprio 0
	v_add_f32_e32 v170, v170, v171
	v_add_f32_e32 v172, v172, v173
	v_add_f32_e32 v170, v170, v172
	v_add_f32_e32 v174, v174, v170
	s_waitcnt lgkmcnt(0)
	s_setprio 1
	v_mfma_f32_32x32x16_bf16 v[112:127], v[128:131], v[224:227], v[112:127]
	v_exp_f32_e32 v192, v192
	v_exp_f32_e32 v193, v193
	ds_read_b64_tr_b16 v[208:209], v162 offset:50176
	ds_read_b64_tr_b16 v[210:211], v162 offset:52736
	v_add_f32_e32 v170, v192, v193
	v_cvt_pk_bf16_f32 v192, v192, v193
	v_mfma_f32_32x32x16_bf16 v[96:111], v[128:131], v[228:231], v[96:111]
	v_exp_f32_e32 v194, v194
	v_exp_f32_e32 v195, v195
	s_nop 0
	v_add_f32_e32 v171, v194, v195
	v_cvt_pk_bf16_f32 v193, v194, v195
	v_mfma_f32_32x32x16_bf16 v[80:95], v[128:131], v[232:235], v[80:95]
	v_exp_f32_e32 v196, v196
	v_exp_f32_e32 v197, v197
	ds_read_b64_tr_b16 v[212:213], v162 offset:50240
	ds_read_b64_tr_b16 v[214:215], v162 offset:52800
	v_add_f32_e32 v172, v196, v197
	v_cvt_pk_bf16_f32 v194, v196, v197
	v_mfma_f32_32x32x16_bf16 v[64:79], v[128:131], v[246:249], v[64:79]
	v_exp_f32_e32 v198, v198
	v_exp_f32_e32 v199, v199
	s_nop 0
	v_add_f32_e32 v173, v198, v199
	v_cvt_pk_bf16_f32 v195, v198, v199
	s_setprio 0
	v_add_f32_e32 v170, v170, v171
	v_add_f32_e32 v172, v172, v173
	v_add_f32_e32 v170, v170, v172
	v_add_f32_e32 v175, v175, v170
	s_waitcnt lgkmcnt(4)
	s_setprio 1
	v_mfma_f32_32x32x16_bf16 v[48:63], v[192:195], v[224:227], v[48:63]
	v_exp_f32_e32 v136, v136
	v_exp_f32_e32 v137, v137
	ds_read_b64_tr_b16 v[250:251], v162 offset:50304
	ds_read_b64_tr_b16 v[252:253], v162 offset:52864
	v_add_f32_e32 v170, v136, v137
	v_cvt_pk_bf16_f32 v136, v136, v137
	v_mfma_f32_32x32x16_bf16 v[32:47], v[192:195], v[228:231], v[32:47]
	v_exp_f32_e32 v138, v138
	v_exp_f32_e32 v139, v139
	s_nop 0
	v_add_f32_e32 v171, v138, v139
	v_cvt_pk_bf16_f32 v137, v138, v139
	v_mfma_f32_32x32x16_bf16 v[16:31], v[192:195], v[232:235], v[16:31]
	v_exp_f32_e32 v140, v140
	v_exp_f32_e32 v141, v141
	ds_read_b64_tr_b16 v[166:167], v162 offset:50368
	ds_read_b64_tr_b16 v[168:169], v162 offset:52928
	v_add_f32_e32 v172, v140, v141
	v_cvt_pk_bf16_f32 v138, v140, v141
	v_mfma_f32_32x32x16_bf16 v[0:15], v[192:195], v[246:249], v[0:15]
	v_exp_f32_e32 v142, v142
	v_exp_f32_e32 v143, v143
	s_nop 0
	v_add_f32_e32 v173, v142, v143
	v_cvt_pk_bf16_f32 v139, v142, v143
	s_setprio 0
	v_add_f32_e32 v170, v170, v171
	v_add_f32_e32 v172, v172, v173
	v_add_f32_e32 v170, v170, v172
	v_add_f32_e32 v174, v174, v170
	s_waitcnt lgkmcnt(0)
	s_setprio 1
	v_mfma_f32_32x32x16_bf16 v[112:127], v[136:139], v[208:211], v[112:127]
	v_exp_f32_e32 v200, v200
	v_exp_f32_e32 v201, v201
	s_nop 0
	v_add_f32_e32 v170, v200, v201
	v_cvt_pk_bf16_f32 v200, v200, v201
	v_mfma_f32_32x32x16_bf16 v[96:111], v[136:139], v[212:215], v[96:111]
	v_exp_f32_e32 v202, v202
	v_exp_f32_e32 v203, v203
	s_nop 0
	v_add_f32_e32 v171, v202, v203
	v_cvt_pk_bf16_f32 v201, v202, v203
	v_mfma_f32_32x32x16_bf16 v[80:95], v[136:139], v[250:253], v[80:95]
	v_exp_f32_e32 v204, v204
	v_exp_f32_e32 v205, v205
	s_nop 0
	v_add_f32_e32 v172, v204, v205
	v_cvt_pk_bf16_f32 v202, v204, v205
	v_mfma_f32_32x32x16_bf16 v[64:79], v[136:139], v[166:169], v[64:79]
	v_exp_f32_e32 v206, v206
	v_exp_f32_e32 v207, v207
	s_nop 0
	v_add_f32_e32 v173, v206, v207
	v_cvt_pk_bf16_f32 v203, v206, v207
	s_setprio 0
	v_add_f32_e32 v170, v170, v171
	v_add_f32_e32 v172, v172, v173
	v_add_f32_e32 v170, v170, v172
	v_add_f32_e32 v175, v175, v170
	s_waitcnt lgkmcnt(0)
	s_setprio 1
	v_mfma_f32_32x32x16_bf16 v[48:63], v[200:203], v[208:211], v[48:63]
	v_mfma_f32_32x32x16_bf16 v[32:47], v[200:203], v[212:215], v[32:47]
	v_mfma_f32_32x32x16_bf16 v[16:31], v[200:203], v[250:253], v[16:31]
	v_mfma_f32_32x32x16_bf16 v[0:15], v[200:203], v[166:169], v[0:15]
	s_setprio 0
	s_waitcnt vmcnt(0)
	s_add_u32 s6, s6, 0x20000
	s_addc_u32 s7, s7, 0
	s_cmp_eq_u32 s10, s11
	s_barrier
	s_cbranch_scc1 .LBB0_126
